# P0: CACT rows dealt from the top of the wave range (workgroups 224..255, which carry one weight-conversion item less) instead of workgroups 0..31
# baseline (speedup 1.0000x reference)
.LBB0_28:
	s_sub_i32 s98, s22, s34
	s_add_i32 s98, s98, -1
	s_cmpk_gt_i32 s98, 0xff
	s_cbranch_scc1 .LBB0_50
	s_waitcnt lgkmcnt(0)
	s_load_dwordx4 s[8:11], s[0:1], 0x28
	s_ashr_i32 s99, s98, 31
	s_lshl_b64 s[4:5], s[98:99], 13
	v_mov_b32_e32 v9, 0
	v_lshlrev_b32_e32 v8, 3, v162
	s_waitcnt lgkmcnt(0)
	s_add_u32 s4, s10, s4
	s_addc_u32 s5, s11, s5
	s_ashr_i32 s23, s22, 31
	s_lshl_b64 s[10:11], s[22:23], 13
	s_lshl_b64 s[6:7], s[98:99], 12
	s_add_u32 s6, s26, s6
	s_addc_u32 s7, s27, s7
	v_lshlrev_b32_e32 v2, 2, v162
	v_lshl_add_u64 v[4:5], s[6:7], 0, v[8:9]
	s_mov_b64 s[6:7], 0xdd00000
	v_lshl_add_u64 v[10:11], v[4:5], 0, s[6:7]
	s_lshl_b64 s[12:13], s[22:23], 12
	s_mov_b32 s15, 0
	v_lshlrev_b32_e32 v8, 2, v2
	s_mov_b32 s3, s98
	s_branch .LBB0_31
